# P2 prologue: max|T5 table - c15| per head computed by the whole wave in parallel (was a 96-iteration serial LDS loop in 8 lanes while the workgroup waited)
# speedup vs baseline: 1.0127x; 1.0056x over previous
; #define LAS __attribute__((address_space(3)))
; __device__ __forceinline__ unsigned ldu(const unsigned* p) { return __hip_atomic_load(p, __ATOMIC_RELAXED, __HIP_MEMORY_SCOPE_AGENT); }
; __global__ void __launch_bounds__(NWAVES * 64, LBW) fwd_kernel(Args A) {
;     ...
;         if (wave == 0) {
;             unsigned ok = 0u;
;             if (lane < 8) { const int hh = lane >> 1;
;                 const float qn2 = __uint_as_float(ldu(ctl + CW_NRM + 32 + lane * 2)) + __uint_as_float(ldu(ctl + CW_NRM + 32 + lane * 2 + 1)), kn2 = __uint_as_float(ldu(ctl + CW_NRM + 48 + lane * 2)) + __uint_as_float(ldu(ctl + CW_NRM + 48 + lane * 2 + 1));
;                 float tb = 0.f; for (int i = 0; i < 192; ++i) tb = fmaxf(tb, fabsf(tabw[hh * 192 + i] - tabw[hh * 192]));
;                 ok = (1.01f * sqrtf(qn2 * kn2) + tb <= 100.0f) ? 1u : 0u; }
;             else if (lane < 16) { const int fh = lane - 8;
;                 const float qn2 = __uint_as_float(ldu(ctl + CW_NRM + fh * 2)) + __uint_as_float(ldu(ctl + CW_NRM + fh * 2 + 1)), kn2 = __uint_as_float(ldu(ctl + CW_NRM + 16 + fh * 2)) + __uint_as_float(ldu(ctl + CW_NRM + 16 + fh * 2 + 1));
;                 ok = (1.01f * sqrtf(qn2 * kn2) <= 100.0f) ? 1u : 0u; }
;             const unsigned long long bal = __ballot(ok != 0u);
;             if (lane == 0) ((LAS unsigned*)misc)[5] = (unsigned)(bal & 0xffffu);
.LBB0_279:
	s_andn2_saveexec_b64 s[6:7], s[6:7]
	s_cbranch_execz .LBB0_287
	v_lshlrev_b32_e32 v1, 3, v194
	global_load_dword v2, v1, s[94:95] offset:2176 sc1
	global_load_dword v4, v1, s[94:95] offset:2180 sc1
	global_load_dword v3, v1, s[94:95] offset:2240 sc1
	global_load_dword v5, v1, s[94:95] offset:2244 sc1
	s_mov_b64 s[98:99], exec
	s_mov_b64 exec, -1
	v_lshrrev_b32_e32 v9, 4, v194
	v_and_b32_e32 v8, 15, v194
	v_lshlrev_b32_e32 v17, 2, v9
	v_mul_u32_u24_e32 v9, 0x300, v9
	v_lshl_add_u32 v8, v8, 2, v9
	v_add_u32_e32 v8, 0x20400, v8
	v_add_u32_e32 v9, 0x20400, v9
	ds_read_b32 v6, v9
	ds_read_b32 v10, v8
	ds_read_b32 v11, v8 offset:64
	ds_read_b32 v12, v8 offset:128
	ds_read_b32 v13, v8 offset:192
	ds_read_b32 v14, v8 offset:256
	ds_read_b32 v15, v8 offset:320
	ds_read_b32 v16, v8 offset:384
	s_waitcnt lgkmcnt(0)
	v_sub_f32_e32 v10, v10, v6
	v_sub_f32_e32 v11, v11, v6
	v_sub_f32_e32 v12, v12, v6
	v_sub_f32_e32 v13, v13, v6
	v_sub_f32_e32 v14, v14, v6
	v_sub_f32_e32 v15, v15, v6
	v_sub_f32_e32 v16, v16, v6
	v_max_f32_e64 v7, |v10|, |v11|
	v_max_f32_e64 v7, v7, |v12|
	v_max_f32_e64 v7, v7, |v13|
	v_max_f32_e64 v7, v7, |v14|
	v_max_f32_e64 v7, v7, |v15|
	v_max_f32_e64 v7, v7, |v16|
	ds_read_b32 v10, v8 offset:448
	ds_read_b32 v11, v8 offset:512
	ds_read_b32 v12, v8 offset:576
	ds_read_b32 v13, v8 offset:640
	ds_read_b32 v14, v8 offset:704
	s_waitcnt lgkmcnt(0)
	v_sub_f32_e32 v10, v10, v6
	v_sub_f32_e32 v11, v11, v6
	v_sub_f32_e32 v12, v12, v6
	v_sub_f32_e32 v13, v13, v6
	v_sub_f32_e32 v14, v14, v6
	v_max_f32_e64 v7, v7, |v10|
	v_max_f32_e64 v7, v7, |v11|
	v_max_f32_e64 v7, v7, |v12|
	v_max_f32_e64 v7, v7, |v13|
	v_max_f32_e64 v7, v7, |v14|
	s_nop 1
	v_max_f32_dpp v7, v7, v7 quad_perm:[1,0,3,2] row_mask:0xf bank_mask:0xf bound_ctrl:1
	s_nop 1
	v_max_f32_dpp v7, v7, v7 quad_perm:[2,3,0,1] row_mask:0xf bank_mask:0xf bound_ctrl:1
	s_nop 1
	v_max_f32_dpp v7, v7, v7 row_half_mirror row_mask:0xf bank_mask:0xf bound_ctrl:1
	s_nop 1
	v_max_f32_dpp v7, v7, v7 row_mirror row_mask:0xf bank_mask:0xf bound_ctrl:1
	s_nop 1
	ds_write_b32 v17, v7
	s_waitcnt lgkmcnt(0)
	s_mov_b64 exec, s[98:99]
	v_lshrrev_b32_e32 v8, 1, v194
	v_lshlrev_b32_e32 v8, 2, v8
	ds_read_b32 v7, v8
	s_waitcnt lgkmcnt(0)
	s_waitcnt vmcnt(0)
	v_pk_add_f32 v[2:3], v[2:3], v[4:5]
	s_mov_b32 s0, 0xf800000
	v_mul_f32_e32 v1, v2, v3
	v_mul_f32_e32 v2, 0x4f800000, v1
	v_cmp_gt_f32_e32 vcc, s0, v1
	s_mov_b32 s0, 0x42c80000
	s_nop 0
	v_cndmask_b32_e32 v1, v1, v2, vcc
	v_sqrt_f32_e32 v2, v1
	s_nop 0
	v_add_u32_e32 v3, -1, v2
	v_fma_f32 v4, -v3, v2, v1
	v_cmp_ge_f32_e64 s[2:3], 0, v4
	v_add_u32_e32 v4, 1, v2
	s_nop 0
	v_cndmask_b32_e64 v3, v2, v3, s[2:3]
	v_fma_f32 v2, -v4, v2, v1
	v_cmp_lt_f32_e64 s[2:3], 0, v2
	s_nop 1
	v_cndmask_b32_e64 v2, v3, v4, s[2:3]
	v_mul_f32_e32 v3, 0x37800000, v2
	v_cndmask_b32_e32 v2, v2, v3, vcc
	v_mov_b32_e32 v3, 0x260
	v_cmp_class_f32_e32 vcc, v1, v3
	s_nop 1
	v_cndmask_b32_e32 v1, v2, v1, vcc
	v_fmamk_f32 v1, v1, 0x3f8147ae, v7
	v_cmp_ge_f32_e32 vcc, s0, v1
	s_andn2_b64 s[0:1], s[4:5], exec
	s_and_b64 s[2:3], vcc, exec
	s_or_b64 s[4:5], s[0:1], s[2:3]
